# v27 with the MFMA-to-VALU spacing before the partial pack kept at 12 wait states (s_nop 9 after two MFMAs)
# baseline (speedup 1.0000x reference)
.Lp2b_in_5:
	v_mfma_f32_32x32x16_bf16 v[2:17], v[118:121], v[150:153], v[2:17]
	v_mfma_f32_32x32x16_bf16 v[2:17], v[122:125], v[154:157], v[2:17]
	s_nop 9
	v_cvt_pk_bf16_f32 v18, v18, v19
	v_cvt_pk_bf16_f32 v19, v20, v21
	v_cvt_pk_bf16_f32 v20, v22, v23
	v_cvt_pk_bf16_f32 v21, v24, v25
	v_cvt_pk_bf16_f32 v22, v26, v27
	v_cvt_pk_bf16_f32 v23, v28, v29
	v_cvt_pk_bf16_f32 v24, v30, v31
	v_cvt_pk_bf16_f32 v25, v32, v33
	ds_write_b128 v192, v[18:21]
	ds_write_b128 v192, v[22:25] offset:1024
	v_mfma_f32_32x32x16_bf16 v[2:17], v[126:129], v[158:161], v[2:17]
	v_cvt_pk_bf16_f32 v34, v34, v35
	v_cvt_pk_bf16_f32 v35, v36, v37
	v_cvt_pk_bf16_f32 v36, v38, v39
	v_cvt_pk_bf16_f32 v37, v40, v41
	v_cvt_pk_bf16_f32 v38, v42, v43
	v_cvt_pk_bf16_f32 v39, v44, v45
	v_cvt_pk_bf16_f32 v40, v46, v47
	v_cvt_pk_bf16_f32 v41, v48, v49
	ds_write_b128 v192, v[34:37] offset:2048
	ds_write_b128 v192, v[38:41] offset:3072
	v_mfma_f32_32x32x16_bf16 v[2:17], v[130:133], v[162:165], v[2:17]
	s_waitcnt lgkmcnt(0)
	s_barrier
	ds_read2st64_b64 v[18:21], v193 offset0:0 offset1:8
	ds_read2st64_b64 v[22:25], v193 offset0:16 offset1:24
	ds_read2st64_b64 v[26:29], v193 offset0:32 offset1:40
	ds_read2st64_b64 v[30:33], v193 offset0:48 offset1:56
	ds_read_b128 v[150:153], v195 offset:4096
	ds_read_b128 v[154:157], v195 offset:5120
	ds_read_b128 v[158:161], v195 offset:6144
	ds_read_b128 v[162:165], v195 offset:7168
	ds_read_b128 v[166:169], v196 offset:4096
	s_waitcnt lgkmcnt(8)
	v_lshlrev_b32_e32 v178, 16, v18
	v_and_b32_e32 v179, 0xffff0000, v18
	v_lshlrev_b32_e32 v180, 16, v19
	v_and_b32_e32 v181, 0xffff0000, v19
	v_add_f32_e32 v174, 0, v178
	v_add_f32_e32 v175, 0, v179
	v_add_f32_e32 v176, 0, v180
	v_add_f32_e32 v177, 0, v181
	v_lshlrev_b32_e32 v178, 16, v20
	v_and_b32_e32 v179, 0xffff0000, v20
	v_lshlrev_b32_e32 v180, 16, v21
	v_and_b32_e32 v181, 0xffff0000, v21
	v_add_f32_e32 v174, v174, v178
	v_add_f32_e32 v175, v175, v179
	v_add_f32_e32 v176, v176, v180
	v_add_f32_e32 v177, v177, v181
	s_waitcnt lgkmcnt(7)
	v_lshlrev_b32_e32 v178, 16, v22
	v_and_b32_e32 v179, 0xffff0000, v22
	v_lshlrev_b32_e32 v180, 16, v23
	v_and_b32_e32 v181, 0xffff0000, v23
	v_add_f32_e32 v174, v174, v178
	v_add_f32_e32 v175, v175, v179
	v_add_f32_e32 v176, v176, v180
	v_add_f32_e32 v177, v177, v181
	v_lshlrev_b32_e32 v178, 16, v24
	v_and_b32_e32 v179, 0xffff0000, v24
	v_lshlrev_b32_e32 v180, 16, v25
	v_and_b32_e32 v181, 0xffff0000, v25
	v_add_f32_e32 v174, v174, v178
	v_add_f32_e32 v175, v175, v179
	v_add_f32_e32 v176, v176, v180
	v_add_f32_e32 v177, v177, v181
	s_waitcnt lgkmcnt(6)
	v_lshlrev_b32_e32 v178, 16, v26
	v_and_b32_e32 v179, 0xffff0000, v26
	v_lshlrev_b32_e32 v180, 16, v27
	v_and_b32_e32 v181, 0xffff0000, v27
	v_add_f32_e32 v174, v174, v178
	v_add_f32_e32 v175, v175, v179
	v_add_f32_e32 v176, v176, v180
	v_add_f32_e32 v177, v177, v181
	v_lshlrev_b32_e32 v178, 16, v28
	v_and_b32_e32 v179, 0xffff0000, v28
	v_lshlrev_b32_e32 v180, 16, v29
	v_and_b32_e32 v181, 0xffff0000, v29
	v_add_f32_e32 v174, v174, v178
	v_add_f32_e32 v175, v175, v179
	v_add_f32_e32 v176, v176, v180
	v_add_f32_e32 v177, v177, v181
	s_waitcnt lgkmcnt(5)
	v_lshlrev_b32_e32 v178, 16, v30
	v_and_b32_e32 v179, 0xffff0000, v30
	v_lshlrev_b32_e32 v180, 16, v31
	v_and_b32_e32 v181, 0xffff0000, v31
	v_add_f32_e32 v174, v174, v178
	v_add_f32_e32 v175, v175, v179
	v_add_f32_e32 v176, v176, v180
	v_add_f32_e32 v177, v177, v181
	v_lshlrev_b32_e32 v178, 16, v32
	v_and_b32_e32 v179, 0xffff0000, v32
	v_lshlrev_b32_e32 v180, 16, v33
	v_and_b32_e32 v181, 0xffff0000, v33
	v_add_f32_e32 v174, v174, v178
	v_add_f32_e32 v175, v175, v179
	v_add_f32_e32 v176, v176, v180
	v_add_f32_e32 v177, v177, v181
	v_mul_f32_e32 v174, v186, v174
	v_mul_f32_e32 v175, v187, v175
	v_mul_f32_e32 v176, v188, v176
	v_mul_f32_e32 v177, v189, v177
	v_bfe_u32 v178, v174, 16, 1
	v_bfe_u32 v179, v175, 16, 1
	v_bfe_u32 v180, v176, 16, 1
	v_bfe_u32 v181, v177, 16, 1
	v_add3_u32 v174, v174, v178, s23
	v_add3_u32 v175, v175, v179, s23
	v_add3_u32 v176, v176, v180, s23
	v_add3_u32 v177, v177, v181, s23
	global_store_short_d16_hi v197, v174, s[20:21] offset:-4096
	global_store_short_d16_hi v197, v175, s[20:21]
	global_store_short_d16_hi v198, v176, s[20:21] offset:-4096
	global_store_short_d16_hi v198, v177, s[20:21]
	s_add_u32 s20, s20, 0x40000
	s_addc_u32 s21, s21, 0
	s_waitcnt vmcnt(9)
	s_andn2_b64 vcc, exec, s[34:35]
	s_cbranch_vccnz .Lp2b_sv_6
	ds_write_b128 v194, v[170:173]
	global_load_dwordx4 v[170:173], v1, s[16:17]

.Lp2b_in_8:
	v_mfma_f32_32x32x16_bf16 v[2:17], v[134:137], v[150:153], v[2:17]
	v_mfma_f32_32x32x16_bf16 v[2:17], v[138:141], v[154:157], v[2:17]
	s_nop 9
	v_cvt_pk_bf16_f32 v18, v18, v19
	v_cvt_pk_bf16_f32 v19, v20, v21
	v_cvt_pk_bf16_f32 v20, v22, v23
	v_cvt_pk_bf16_f32 v21, v24, v25
	v_cvt_pk_bf16_f32 v22, v26, v27
	v_cvt_pk_bf16_f32 v23, v28, v29
	v_cvt_pk_bf16_f32 v24, v30, v31
	v_cvt_pk_bf16_f32 v25, v32, v33
	ds_write_b128 v192, v[18:21] offset:32768
	ds_write_b128 v192, v[22:25] offset:33792
	v_mfma_f32_32x32x16_bf16 v[2:17], v[142:145], v[158:161], v[2:17]
	v_cvt_pk_bf16_f32 v34, v34, v35
	v_cvt_pk_bf16_f32 v35, v36, v37
	v_cvt_pk_bf16_f32 v36, v38, v39
	v_cvt_pk_bf16_f32 v37, v40, v41
	v_cvt_pk_bf16_f32 v38, v42, v43
	v_cvt_pk_bf16_f32 v39, v44, v45
	v_cvt_pk_bf16_f32 v40, v46, v47
	v_cvt_pk_bf16_f32 v41, v48, v49
	ds_write_b128 v192, v[34:37] offset:34816
	ds_write_b128 v192, v[38:41] offset:35840
	v_mfma_f32_32x32x16_bf16 v[2:17], v[146:149], v[162:165], v[2:17]
	s_waitcnt lgkmcnt(0)
	s_barrier
	ds_read2st64_b64 v[18:21], v193 offset0:64 offset1:72
	ds_read2st64_b64 v[22:25], v193 offset0:80 offset1:88
	ds_read2st64_b64 v[26:29], v193 offset0:96 offset1:104
	ds_read2st64_b64 v[30:33], v193 offset0:112 offset1:120
	ds_read_b128 v[150:153], v195
	ds_read_b128 v[154:157], v195 offset:1024
	ds_read_b128 v[158:161], v195 offset:2048
	ds_read_b128 v[162:165], v195 offset:3072
	ds_read_b128 v[166:169], v196
	s_waitcnt lgkmcnt(8)
	v_lshlrev_b32_e32 v178, 16, v18
	v_and_b32_e32 v179, 0xffff0000, v18
	v_lshlrev_b32_e32 v180, 16, v19
	v_and_b32_e32 v181, 0xffff0000, v19
	v_add_f32_e32 v174, 0, v178
	v_add_f32_e32 v175, 0, v179
	v_add_f32_e32 v176, 0, v180
	v_add_f32_e32 v177, 0, v181
	v_lshlrev_b32_e32 v178, 16, v20
	v_and_b32_e32 v179, 0xffff0000, v20
	v_lshlrev_b32_e32 v180, 16, v21
	v_and_b32_e32 v181, 0xffff0000, v21
	v_add_f32_e32 v174, v174, v178
	v_add_f32_e32 v175, v175, v179
	v_add_f32_e32 v176, v176, v180
	v_add_f32_e32 v177, v177, v181
	s_waitcnt lgkmcnt(7)
	v_lshlrev_b32_e32 v178, 16, v22
	v_and_b32_e32 v179, 0xffff0000, v22
	v_lshlrev_b32_e32 v180, 16, v23
	v_and_b32_e32 v181, 0xffff0000, v23
	v_add_f32_e32 v174, v174, v178
	v_add_f32_e32 v175, v175, v179
	v_add_f32_e32 v176, v176, v180
	v_add_f32_e32 v177, v177, v181
	v_lshlrev_b32_e32 v178, 16, v24
	v_and_b32_e32 v179, 0xffff0000, v24
	v_lshlrev_b32_e32 v180, 16, v25
	v_and_b32_e32 v181, 0xffff0000, v25
	v_add_f32_e32 v174, v174, v178
	v_add_f32_e32 v175, v175, v179
	v_add_f32_e32 v176, v176, v180
	v_add_f32_e32 v177, v177, v181
	s_waitcnt lgkmcnt(6)
	v_lshlrev_b32_e32 v178, 16, v26
	v_and_b32_e32 v179, 0xffff0000, v26
	v_lshlrev_b32_e32 v180, 16, v27
	v_and_b32_e32 v181, 0xffff0000, v27
	v_add_f32_e32 v174, v174, v178
	v_add_f32_e32 v175, v175, v179
	v_add_f32_e32 v176, v176, v180
	v_add_f32_e32 v177, v177, v181
	v_lshlrev_b32_e32 v178, 16, v28
	v_and_b32_e32 v179, 0xffff0000, v28
	v_lshlrev_b32_e32 v180, 16, v29
	v_and_b32_e32 v181, 0xffff0000, v29
	v_add_f32_e32 v174, v174, v178
	v_add_f32_e32 v175, v175, v179
	v_add_f32_e32 v176, v176, v180
	v_add_f32_e32 v177, v177, v181
	s_waitcnt lgkmcnt(5)
	v_lshlrev_b32_e32 v178, 16, v30
	v_and_b32_e32 v179, 0xffff0000, v30
	v_lshlrev_b32_e32 v180, 16, v31
	v_and_b32_e32 v181, 0xffff0000, v31
	v_add_f32_e32 v174, v174, v178
	v_add_f32_e32 v175, v175, v179
	v_add_f32_e32 v176, v176, v180
	v_add_f32_e32 v177, v177, v181
	v_lshlrev_b32_e32 v178, 16, v32
	v_and_b32_e32 v179, 0xffff0000, v32
	v_lshlrev_b32_e32 v180, 16, v33
	v_and_b32_e32 v181, 0xffff0000, v33
	v_add_f32_e32 v174, v174, v178
	v_add_f32_e32 v175, v175, v179
	v_add_f32_e32 v176, v176, v180
	v_add_f32_e32 v177, v177, v181
	v_mul_f32_e32 v174, v186, v174
	v_mul_f32_e32 v175, v187, v175
	v_mul_f32_e32 v176, v188, v176
	v_mul_f32_e32 v177, v189, v177
	v_bfe_u32 v178, v174, 16, 1
	v_bfe_u32 v179, v175, 16, 1
	v_bfe_u32 v180, v176, 16, 1
	v_bfe_u32 v181, v177, 16, 1
	v_add3_u32 v174, v174, v178, s23
	v_add3_u32 v175, v175, v179, s23
	v_add3_u32 v176, v176, v180, s23
	v_add3_u32 v177, v177, v181, s23
	global_store_short_d16_hi v197, v174, s[20:21] offset:-4096
	global_store_short_d16_hi v197, v175, s[20:21]
	global_store_short_d16_hi v198, v176, s[20:21] offset:-4096
	global_store_short_d16_hi v198, v177, s[20:21]
	s_add_u32 s20, s20, 0x40000
	s_addc_u32 s21, s21, 0
	s_waitcnt vmcnt(9)
	s_andn2_b64 vcc, exec, s[34:35]
	s_cbranch_vccnz .Lp2b_sv_9
	ds_write_b128 v194, v[170:173] offset:4096
	global_load_dwordx4 v[170:173], v1, s[16:17]

; __device__ __forceinline__ void scan_phase(const bf16* q, const bf16* kdT, const bf16* vT, const bf16* Pp, bf16* o, LAS unsigned char* lds, int bid, int G, int wave, int lane, int tid) {
;     ...
;         for (int i = 0; i < 60; i += 6) { SCAN_STEP(0, 2, 0, 1, i); SCAN_STEP(1, 0, 1, 0, i + 1); SCAN_STEP(2, 1, 0, 1, i + 2); SCAN_STEP(0, 2, 1, 0, i + 3); SCAN_STEP(1, 0, 0, 1, i + 4); SCAN_STEP(2, 1, 1, 0, i + 5); }
.Lp2b_in_20:
	v_mfma_f32_32x32x16_bf16 v[2:17], v[134:137], v[150:153], v[2:17]
	v_mfma_f32_32x32x16_bf16 v[2:17], v[138:141], v[154:157], v[2:17]
	s_nop 9
	v_cvt_pk_bf16_f32 v18, v18, v19
	v_cvt_pk_bf16_f32 v19, v20, v21
	v_cvt_pk_bf16_f32 v20, v22, v23
	v_cvt_pk_bf16_f32 v21, v24, v25
	v_cvt_pk_bf16_f32 v22, v26, v27
	v_cvt_pk_bf16_f32 v23, v28, v29
	v_cvt_pk_bf16_f32 v24, v30, v31
	v_cvt_pk_bf16_f32 v25, v32, v33
	ds_write_b128 v192, v[18:21] offset:32768
	ds_write_b128 v192, v[22:25] offset:33792
	v_mfma_f32_32x32x16_bf16 v[2:17], v[142:145], v[158:161], v[2:17]
	v_cvt_pk_bf16_f32 v34, v34, v35
	v_cvt_pk_bf16_f32 v35, v36, v37
	v_cvt_pk_bf16_f32 v36, v38, v39
	v_cvt_pk_bf16_f32 v37, v40, v41
	v_cvt_pk_bf16_f32 v38, v42, v43
	v_cvt_pk_bf16_f32 v39, v44, v45
	v_cvt_pk_bf16_f32 v40, v46, v47
	v_cvt_pk_bf16_f32 v41, v48, v49
	ds_write_b128 v192, v[34:37] offset:34816
	ds_write_b128 v192, v[38:41] offset:35840
	v_mfma_f32_32x32x16_bf16 v[2:17], v[146:149], v[162:165], v[2:17]
	s_waitcnt lgkmcnt(0)
	s_barrier
	ds_read2st64_b64 v[18:21], v193 offset0:64 offset1:72
	ds_read2st64_b64 v[22:25], v193 offset0:80 offset1:88
	ds_read2st64_b64 v[26:29], v193 offset0:96 offset1:104
	ds_read2st64_b64 v[30:33], v193 offset0:112 offset1:120
	ds_read_b128 v[150:153], v195
	ds_read_b128 v[154:157], v195 offset:1024
	ds_read_b128 v[158:161], v195 offset:2048
	ds_read_b128 v[162:165], v195 offset:3072
	ds_read_b128 v[166:169], v196
	s_waitcnt lgkmcnt(8)
	v_lshlrev_b32_e32 v178, 16, v18
	v_and_b32_e32 v179, 0xffff0000, v18
	v_lshlrev_b32_e32 v180, 16, v19
	v_and_b32_e32 v181, 0xffff0000, v19
	v_add_f32_e32 v174, 0, v178
	v_add_f32_e32 v175, 0, v179
	v_add_f32_e32 v176, 0, v180
	v_add_f32_e32 v177, 0, v181
	v_lshlrev_b32_e32 v178, 16, v20
	v_and_b32_e32 v179, 0xffff0000, v20
	v_lshlrev_b32_e32 v180, 16, v21
	v_and_b32_e32 v181, 0xffff0000, v21
	v_add_f32_e32 v174, v174, v178
	v_add_f32_e32 v175, v175, v179
	v_add_f32_e32 v176, v176, v180
	v_add_f32_e32 v177, v177, v181
	s_waitcnt lgkmcnt(7)
	v_lshlrev_b32_e32 v178, 16, v22
	v_and_b32_e32 v179, 0xffff0000, v22
	v_lshlrev_b32_e32 v180, 16, v23
	v_and_b32_e32 v181, 0xffff0000, v23
	v_add_f32_e32 v174, v174, v178
	v_add_f32_e32 v175, v175, v179
	v_add_f32_e32 v176, v176, v180
	v_add_f32_e32 v177, v177, v181
	v_lshlrev_b32_e32 v178, 16, v24
	v_and_b32_e32 v179, 0xffff0000, v24
	v_lshlrev_b32_e32 v180, 16, v25
	v_and_b32_e32 v181, 0xffff0000, v25
	v_add_f32_e32 v174, v174, v178
	v_add_f32_e32 v175, v175, v179
	v_add_f32_e32 v176, v176, v180
	v_add_f32_e32 v177, v177, v181
	s_waitcnt lgkmcnt(6)
	v_lshlrev_b32_e32 v178, 16, v26
	v_and_b32_e32 v179, 0xffff0000, v26
	v_lshlrev_b32_e32 v180, 16, v27
	v_and_b32_e32 v181, 0xffff0000, v27
	v_add_f32_e32 v174, v174, v178
	v_add_f32_e32 v175, v175, v179
	v_add_f32_e32 v176, v176, v180
	v_add_f32_e32 v177, v177, v181
	v_lshlrev_b32_e32 v178, 16, v28
	v_and_b32_e32 v179, 0xffff0000, v28
	v_lshlrev_b32_e32 v180, 16, v29
	v_and_b32_e32 v181, 0xffff0000, v29
	v_add_f32_e32 v174, v174, v178
	v_add_f32_e32 v175, v175, v179
	v_add_f32_e32 v176, v176, v180
	v_add_f32_e32 v177, v177, v181
	s_waitcnt lgkmcnt(5)
	v_lshlrev_b32_e32 v178, 16, v30
	v_and_b32_e32 v179, 0xffff0000, v30
	v_lshlrev_b32_e32 v180, 16, v31
	v_and_b32_e32 v181, 0xffff0000, v31
	v_add_f32_e32 v174, v174, v178
	v_add_f32_e32 v175, v175, v179
	v_add_f32_e32 v176, v176, v180
	v_add_f32_e32 v177, v177, v181
	v_lshlrev_b32_e32 v178, 16, v32
	v_and_b32_e32 v179, 0xffff0000, v32
	v_lshlrev_b32_e32 v180, 16, v33
	v_and_b32_e32 v181, 0xffff0000, v33
	v_add_f32_e32 v174, v174, v178
	v_add_f32_e32 v175, v175, v179
	v_add_f32_e32 v176, v176, v180
	v_add_f32_e32 v177, v177, v181
	v_mul_f32_e32 v174, v186, v174
	v_mul_f32_e32 v175, v187, v175
	v_mul_f32_e32 v176, v188, v176
	v_mul_f32_e32 v177, v189, v177
	v_bfe_u32 v178, v174, 16, 1
	v_bfe_u32 v179, v175, 16, 1
	v_bfe_u32 v180, v176, 16, 1
	v_bfe_u32 v181, v177, 16, 1
	v_add3_u32 v174, v174, v178, s23
	v_add3_u32 v175, v175, v179, s23
	v_add3_u32 v176, v176, v180, s23
	v_add3_u32 v177, v177, v181, s23
	global_store_short_d16_hi v197, v174, s[20:21] offset:-4096
	global_store_short_d16_hi v197, v175, s[20:21]
	global_store_short_d16_hi v198, v176, s[20:21] offset:-4096
	global_store_short_d16_hi v198, v177, s[20:21]
	s_add_u32 s20, s20, 0x40000
	s_addc_u32 s21, s21, 0
	s_add_i32 s22, s22, 1
	s_cmp_lt_u32 s22, 10
	s_cbranch_scc1 .Lp2b_loop
	s_waitcnt vmcnt(9)
	s_andn2_b64 vcc, exec, s[34:35]
	s_cbranch_vccnz .Lp2b_sv_21
	ds_write_b128 v194, v[170:173] offset:4096
	global_load_dwordx4 v[170:173], v1, s[16:17]

; __device__ __forceinline__ void scan_phase(const bf16* q, const bf16* kdT, const bf16* vT, const bf16* Pp, bf16* o, LAS unsigned char* lds, int bid, int G, int wave, int lane, int tid) {
;     ...
;         SCAN_STEP(0, 2, 0, 1, 60); SCAN_STEP(1, 0, 1, 0, 61); SCAN_STEP(2, 1, 0, 1, 62); SCAN_STEP(0, 2, 1, 0, 63);
.Lp2b_in_26:
	v_mfma_f32_32x32x16_bf16 v[2:17], v[134:137], v[150:153], v[2:17]
	v_mfma_f32_32x32x16_bf16 v[2:17], v[138:141], v[154:157], v[2:17]
	s_nop 9
	v_cvt_pk_bf16_f32 v18, v18, v19
	v_cvt_pk_bf16_f32 v19, v20, v21
	v_cvt_pk_bf16_f32 v20, v22, v23
	v_cvt_pk_bf16_f32 v21, v24, v25
	v_cvt_pk_bf16_f32 v22, v26, v27
	v_cvt_pk_bf16_f32 v23, v28, v29
	v_cvt_pk_bf16_f32 v24, v30, v31
	v_cvt_pk_bf16_f32 v25, v32, v33
	ds_write_b128 v192, v[18:21] offset:32768
	ds_write_b128 v192, v[22:25] offset:33792
	v_mfma_f32_32x32x16_bf16 v[2:17], v[142:145], v[158:161], v[2:17]
	v_cvt_pk_bf16_f32 v34, v34, v35
	v_cvt_pk_bf16_f32 v35, v36, v37
	v_cvt_pk_bf16_f32 v36, v38, v39
	v_cvt_pk_bf16_f32 v37, v40, v41
	v_cvt_pk_bf16_f32 v38, v42, v43
	v_cvt_pk_bf16_f32 v39, v44, v45
	v_cvt_pk_bf16_f32 v40, v46, v47
	v_cvt_pk_bf16_f32 v41, v48, v49
	ds_write_b128 v192, v[34:37] offset:34816
	ds_write_b128 v192, v[38:41] offset:35840
	v_mfma_f32_32x32x16_bf16 v[2:17], v[146:149], v[162:165], v[2:17]
	s_waitcnt lgkmcnt(0)
	s_barrier
	ds_read2st64_b64 v[18:21], v193 offset0:64 offset1:72
	ds_read2st64_b64 v[22:25], v193 offset0:80 offset1:88
	ds_read2st64_b64 v[26:29], v193 offset0:96 offset1:104
	ds_read2st64_b64 v[30:33], v193 offset0:112 offset1:120
	ds_read_b128 v[150:153], v195
	ds_read_b128 v[154:157], v195 offset:1024
	ds_read_b128 v[158:161], v195 offset:2048
	ds_read_b128 v[162:165], v195 offset:3072
	ds_read_b128 v[166:169], v196
	s_waitcnt lgkmcnt(8)
	v_lshlrev_b32_e32 v178, 16, v18
	v_and_b32_e32 v179, 0xffff0000, v18
	v_lshlrev_b32_e32 v180, 16, v19
	v_and_b32_e32 v181, 0xffff0000, v19
	v_add_f32_e32 v174, 0, v178
	v_add_f32_e32 v175, 0, v179
	v_add_f32_e32 v176, 0, v180
	v_add_f32_e32 v177, 0, v181
	v_lshlrev_b32_e32 v178, 16, v20
	v_and_b32_e32 v179, 0xffff0000, v20
	v_lshlrev_b32_e32 v180, 16, v21
	v_and_b32_e32 v181, 0xffff0000, v21
	v_add_f32_e32 v174, v174, v178
	v_add_f32_e32 v175, v175, v179
	v_add_f32_e32 v176, v176, v180
	v_add_f32_e32 v177, v177, v181
	s_waitcnt lgkmcnt(7)
	v_lshlrev_b32_e32 v178, 16, v22
	v_and_b32_e32 v179, 0xffff0000, v22
	v_lshlrev_b32_e32 v180, 16, v23
	v_and_b32_e32 v181, 0xffff0000, v23
	v_add_f32_e32 v174, v174, v178
	v_add_f32_e32 v175, v175, v179
	v_add_f32_e32 v176, v176, v180
	v_add_f32_e32 v177, v177, v181
	v_lshlrev_b32_e32 v178, 16, v24
	v_and_b32_e32 v179, 0xffff0000, v24
	v_lshlrev_b32_e32 v180, 16, v25
	v_and_b32_e32 v181, 0xffff0000, v25
	v_add_f32_e32 v174, v174, v178
	v_add_f32_e32 v175, v175, v179
	v_add_f32_e32 v176, v176, v180
	v_add_f32_e32 v177, v177, v181
	s_waitcnt lgkmcnt(6)
	v_lshlrev_b32_e32 v178, 16, v26
	v_and_b32_e32 v179, 0xffff0000, v26
	v_lshlrev_b32_e32 v180, 16, v27
	v_and_b32_e32 v181, 0xffff0000, v27
	v_add_f32_e32 v174, v174, v178
	v_add_f32_e32 v175, v175, v179
	v_add_f32_e32 v176, v176, v180
	v_add_f32_e32 v177, v177, v181
	v_lshlrev_b32_e32 v178, 16, v28
	v_and_b32_e32 v179, 0xffff0000, v28
	v_lshlrev_b32_e32 v180, 16, v29
	v_and_b32_e32 v181, 0xffff0000, v29
	v_add_f32_e32 v174, v174, v178
	v_add_f32_e32 v175, v175, v179
	v_add_f32_e32 v176, v176, v180
	v_add_f32_e32 v177, v177, v181
	s_waitcnt lgkmcnt(5)
	v_lshlrev_b32_e32 v178, 16, v30
	v_and_b32_e32 v179, 0xffff0000, v30
	v_lshlrev_b32_e32 v180, 16, v31
	v_and_b32_e32 v181, 0xffff0000, v31
	v_add_f32_e32 v174, v174, v178
	v_add_f32_e32 v175, v175, v179
	v_add_f32_e32 v176, v176, v180
	v_add_f32_e32 v177, v177, v181
	v_lshlrev_b32_e32 v178, 16, v32
	v_and_b32_e32 v179, 0xffff0000, v32
	v_lshlrev_b32_e32 v180, 16, v33
	v_and_b32_e32 v181, 0xffff0000, v33
	v_add_f32_e32 v174, v174, v178
	v_add_f32_e32 v175, v175, v179
	v_add_f32_e32 v176, v176, v180
	v_add_f32_e32 v177, v177, v181
	v_mul_f32_e32 v174, v186, v174
	v_mul_f32_e32 v175, v187, v175
	v_mul_f32_e32 v176, v188, v176
	v_mul_f32_e32 v177, v189, v177
	v_bfe_u32 v178, v174, 16, 1
	v_bfe_u32 v179, v175, 16, 1
	v_bfe_u32 v180, v176, 16, 1
	v_bfe_u32 v181, v177, 16, 1
	v_add3_u32 v174, v174, v178, s23
	v_add3_u32 v175, v175, v179, s23
	v_add3_u32 v176, v176, v180, s23
	v_add3_u32 v177, v177, v181, s23
	global_store_short_d16_hi v197, v174, s[20:21] offset:-4096
	global_store_short_d16_hi v197, v175, s[20:21]
	global_store_short_d16_hi v198, v176, s[20:21] offset:-4096
	global_store_short_d16_hi v198, v177, s[20:21]
	s_add_u32 s20, s20, 0x40000
	s_addc_u32 s21, s21, 0
	s_waitcnt vmcnt(9)
	s_andn2_b64 vcc, exec, s[34:35]
	s_cbranch_vccnz .Lp2b_sv_27
	ds_write_b128 v194, v[170:173] offset:4096

; __device__ __forceinline__ void scan_phase(const bf16* q, const bf16* kdT, const bf16* vT, const bf16* Pp, bf16* o, LAS unsigned char* lds, int bid, int G, int wave, int lane, int tid) {
;     ...
;         SCAN_STEP(0, 2, 0, 1, 60); SCAN_STEP(1, 0, 1, 0, 61); SCAN_STEP(2, 1, 0, 1, 62); SCAN_STEP(0, 2, 1, 0, 63);
.Lp2b_in_29:
	v_mfma_f32_32x32x16_bf16 v[2:17], v[118:121], v[150:153], v[2:17]
	v_mfma_f32_32x32x16_bf16 v[2:17], v[122:125], v[154:157], v[2:17]
	s_nop 9
	v_cvt_pk_bf16_f32 v18, v18, v19
	v_cvt_pk_bf16_f32 v19, v20, v21
	v_cvt_pk_bf16_f32 v20, v22, v23
	v_cvt_pk_bf16_f32 v21, v24, v25
	v_cvt_pk_bf16_f32 v22, v26, v27
	v_cvt_pk_bf16_f32 v23, v28, v29
	v_cvt_pk_bf16_f32 v24, v30, v31
	v_cvt_pk_bf16_f32 v25, v32, v33
	ds_write_b128 v192, v[18:21]
	ds_write_b128 v192, v[22:25] offset:1024
	v_mfma_f32_32x32x16_bf16 v[2:17], v[126:129], v[158:161], v[2:17]
	v_cvt_pk_bf16_f32 v34, v34, v35
	v_cvt_pk_bf16_f32 v35, v36, v37
	v_cvt_pk_bf16_f32 v36, v38, v39
	v_cvt_pk_bf16_f32 v37, v40, v41
	v_cvt_pk_bf16_f32 v38, v42, v43
	v_cvt_pk_bf16_f32 v39, v44, v45
	v_cvt_pk_bf16_f32 v40, v46, v47
	v_cvt_pk_bf16_f32 v41, v48, v49
	ds_write_b128 v192, v[34:37] offset:2048
	ds_write_b128 v192, v[38:41] offset:3072
	v_mfma_f32_32x32x16_bf16 v[2:17], v[130:133], v[162:165], v[2:17]
	s_waitcnt lgkmcnt(0)
	s_barrier
	ds_read2st64_b64 v[18:21], v193 offset0:0 offset1:8
	ds_read2st64_b64 v[22:25], v193 offset0:16 offset1:24
	ds_read2st64_b64 v[26:29], v193 offset0:32 offset1:40
	ds_read2st64_b64 v[30:33], v193 offset0:48 offset1:56
	ds_read_b128 v[150:153], v195 offset:4096
	ds_read_b128 v[154:157], v195 offset:5120
	ds_read_b128 v[158:161], v195 offset:6144
	ds_read_b128 v[162:165], v195 offset:7168
	ds_read_b128 v[166:169], v196 offset:4096
	s_waitcnt lgkmcnt(8)
	v_lshlrev_b32_e32 v178, 16, v18
	v_and_b32_e32 v179, 0xffff0000, v18
	v_lshlrev_b32_e32 v180, 16, v19
	v_and_b32_e32 v181, 0xffff0000, v19
	v_add_f32_e32 v174, 0, v178
	v_add_f32_e32 v175, 0, v179
	v_add_f32_e32 v176, 0, v180
	v_add_f32_e32 v177, 0, v181
	v_lshlrev_b32_e32 v178, 16, v20
	v_and_b32_e32 v179, 0xffff0000, v20
	v_lshlrev_b32_e32 v180, 16, v21
	v_and_b32_e32 v181, 0xffff0000, v21
	v_add_f32_e32 v174, v174, v178
	v_add_f32_e32 v175, v175, v179
	v_add_f32_e32 v176, v176, v180
	v_add_f32_e32 v177, v177, v181
	s_waitcnt lgkmcnt(7)
	v_lshlrev_b32_e32 v178, 16, v22
	v_and_b32_e32 v179, 0xffff0000, v22
	v_lshlrev_b32_e32 v180, 16, v23
	v_and_b32_e32 v181, 0xffff0000, v23
	v_add_f32_e32 v174, v174, v178
	v_add_f32_e32 v175, v175, v179
	v_add_f32_e32 v176, v176, v180
	v_add_f32_e32 v177, v177, v181
	v_lshlrev_b32_e32 v178, 16, v24
	v_and_b32_e32 v179, 0xffff0000, v24
	v_lshlrev_b32_e32 v180, 16, v25
	v_and_b32_e32 v181, 0xffff0000, v25
	v_add_f32_e32 v174, v174, v178
	v_add_f32_e32 v175, v175, v179
	v_add_f32_e32 v176, v176, v180
	v_add_f32_e32 v177, v177, v181
	s_waitcnt lgkmcnt(6)
	v_lshlrev_b32_e32 v178, 16, v26
	v_and_b32_e32 v179, 0xffff0000, v26
	v_lshlrev_b32_e32 v180, 16, v27
	v_and_b32_e32 v181, 0xffff0000, v27
	v_add_f32_e32 v174, v174, v178
	v_add_f32_e32 v175, v175, v179
	v_add_f32_e32 v176, v176, v180
	v_add_f32_e32 v177, v177, v181
	v_lshlrev_b32_e32 v178, 16, v28
	v_and_b32_e32 v179, 0xffff0000, v28
	v_lshlrev_b32_e32 v180, 16, v29
	v_and_b32_e32 v181, 0xffff0000, v29
	v_add_f32_e32 v174, v174, v178
	v_add_f32_e32 v175, v175, v179
	v_add_f32_e32 v176, v176, v180
	v_add_f32_e32 v177, v177, v181
	s_waitcnt lgkmcnt(5)
	v_lshlrev_b32_e32 v178, 16, v30
	v_and_b32_e32 v179, 0xffff0000, v30
	v_lshlrev_b32_e32 v180, 16, v31
	v_and_b32_e32 v181, 0xffff0000, v31
	v_add_f32_e32 v174, v174, v178
	v_add_f32_e32 v175, v175, v179
	v_add_f32_e32 v176, v176, v180
	v_add_f32_e32 v177, v177, v181
	v_lshlrev_b32_e32 v178, 16, v32
	v_and_b32_e32 v179, 0xffff0000, v32
	v_lshlrev_b32_e32 v180, 16, v33
	v_and_b32_e32 v181, 0xffff0000, v33
	v_add_f32_e32 v174, v174, v178
	v_add_f32_e32 v175, v175, v179
	v_add_f32_e32 v176, v176, v180
	v_add_f32_e32 v177, v177, v181
	v_mul_f32_e32 v174, v186, v174
	v_mul_f32_e32 v175, v187, v175
	v_mul_f32_e32 v176, v188, v176
	v_mul_f32_e32 v177, v189, v177
	v_bfe_u32 v178, v174, 16, 1
	v_bfe_u32 v179, v175, 16, 1
	v_bfe_u32 v180, v176, 16, 1
	v_bfe_u32 v181, v177, 16, 1
	v_add3_u32 v174, v174, v178, s23
	v_add3_u32 v175, v175, v179, s23
	v_add3_u32 v176, v176, v180, s23
	v_add3_u32 v177, v177, v181, s23
	global_store_short_d16_hi v197, v174, s[20:21] offset:-4096
	global_store_short_d16_hi v197, v175, s[20:21]
	global_store_short_d16_hi v198, v176, s[20:21] offset:-4096
	global_store_short_d16_hi v198, v177, s[20:21]
	s_add_u32 s20, s20, 0x40000
	s_addc_u32 s21, s21, 0
	s_waitcnt vmcnt(4)
	v_cvt_pk_bf16_f32 v50, v2, v3
	v_cvt_pk_bf16_f32 v51, v4, v5
	v_cvt_pk_bf16_f32 v52, v6, v7
	v_cvt_pk_bf16_f32 v53, v8, v9
	v_cvt_pk_bf16_f32 v54, v10, v11
	v_cvt_pk_bf16_f32 v55, v12, v13
	v_cvt_pk_bf16_f32 v56, v14, v15
	v_cvt_pk_bf16_f32 v57, v16, v17
	v_mfma_f32_32x32x16_bf16 v[18:33], v[58:61], v[50:53], 0
	v_mfma_f32_32x32x16_bf16 v[34:49], v[66:69], v[50:53], 0
	v_mfma_f32_32x32x16_bf16 v[18:33], v[62:65], v[54:57], v[18:33]
	v_mfma_f32_32x32x16_bf16 v[34:49], v[70:73], v[54:57], v[34:49]
	v_mul_f32_e32 v2, v190, v2
	v_mul_f32_e32 v3, v190, v3
	v_mul_f32_e32 v4, v190, v4
	v_mul_f32_e32 v5, v190, v5
	v_mul_f32_e32 v6, v190, v6
	v_mul_f32_e32 v7, v190, v7
	v_mul_f32_e32 v8, v190, v8
	v_mul_f32_e32 v9, v190, v9
	v_mul_f32_e32 v10, v190, v10
	v_mul_f32_e32 v11, v190, v11
	v_mul_f32_e32 v12, v190, v12
	v_mul_f32_e32 v13, v190, v13
	v_mul_f32_e32 v14, v190, v14
	v_mul_f32_e32 v15, v190, v15
	v_mul_f32_e32 v16, v190, v16
	v_mul_f32_e32 v17, v190, v17
	s_waitcnt lgkmcnt(0)
	s_cmp_eq_u32 s7, 0
	s_cbranch_scc0 .Lp2b_in_30
	v_mfma_f32_32x32x16_bf16 v[18:33], v[74:77], v[166:169], v[18:33]
	s_branch .Lp2b_in_31

; __device__ __forceinline__ void scan_phase(const bf16* q, const bf16* kdT, const bf16* vT, const bf16* Pp, bf16* o, LAS unsigned char* lds, int bid, int G, int wave, int lane, int tid) {
;     ...
;         __syncthreads();
.Lp2b_in_31:
	v_mfma_f32_32x32x16_bf16 v[2:17], v[134:137], v[150:153], v[2:17]
	v_mfma_f32_32x32x16_bf16 v[2:17], v[138:141], v[154:157], v[2:17]
	s_nop 9
	v_cvt_pk_bf16_f32 v18, v18, v19
	v_cvt_pk_bf16_f32 v19, v20, v21
	v_cvt_pk_bf16_f32 v20, v22, v23
	v_cvt_pk_bf16_f32 v21, v24, v25
	v_cvt_pk_bf16_f32 v22, v26, v27
	v_cvt_pk_bf16_f32 v23, v28, v29
	v_cvt_pk_bf16_f32 v24, v30, v31
	v_cvt_pk_bf16_f32 v25, v32, v33
	ds_write_b128 v192, v[18:21] offset:32768
	ds_write_b128 v192, v[22:25] offset:33792
	v_mfma_f32_32x32x16_bf16 v[2:17], v[142:145], v[158:161], v[2:17]
	v_cvt_pk_bf16_f32 v34, v34, v35
	v_cvt_pk_bf16_f32 v35, v36, v37
	v_cvt_pk_bf16_f32 v36, v38, v39
	v_cvt_pk_bf16_f32 v37, v40, v41
	v_cvt_pk_bf16_f32 v38, v42, v43
	v_cvt_pk_bf16_f32 v39, v44, v45
	v_cvt_pk_bf16_f32 v40, v46, v47
	v_cvt_pk_bf16_f32 v41, v48, v49
	ds_write_b128 v192, v[34:37] offset:34816
	ds_write_b128 v192, v[38:41] offset:35840
	v_mfma_f32_32x32x16_bf16 v[2:17], v[146:149], v[162:165], v[2:17]
	s_waitcnt lgkmcnt(0)
	s_barrier
	ds_read2st64_b64 v[18:21], v193 offset0:64 offset1:72
	ds_read2st64_b64 v[22:25], v193 offset0:80 offset1:88
	ds_read2st64_b64 v[26:29], v193 offset0:96 offset1:104
	ds_read2st64_b64 v[30:33], v193 offset0:112 offset1:120
	s_waitcnt lgkmcnt(3)
	v_lshlrev_b32_e32 v178, 16, v18
	v_and_b32_e32 v179, 0xffff0000, v18
	v_lshlrev_b32_e32 v180, 16, v19
	v_and_b32_e32 v181, 0xffff0000, v19
	v_add_f32_e32 v174, 0, v178
	v_add_f32_e32 v175, 0, v179
	v_add_f32_e32 v176, 0, v180
	v_add_f32_e32 v177, 0, v181
	v_lshlrev_b32_e32 v178, 16, v20
	v_and_b32_e32 v179, 0xffff0000, v20
	v_lshlrev_b32_e32 v180, 16, v21
	v_and_b32_e32 v181, 0xffff0000, v21
	v_add_f32_e32 v174, v174, v178
	v_add_f32_e32 v175, v175, v179
	v_add_f32_e32 v176, v176, v180
	v_add_f32_e32 v177, v177, v181
	s_waitcnt lgkmcnt(2)
	v_lshlrev_b32_e32 v178, 16, v22
	v_and_b32_e32 v179, 0xffff0000, v22
	v_lshlrev_b32_e32 v180, 16, v23
	v_and_b32_e32 v181, 0xffff0000, v23
	v_add_f32_e32 v174, v174, v178
	v_add_f32_e32 v175, v175, v179
	v_add_f32_e32 v176, v176, v180
	v_add_f32_e32 v177, v177, v181
	v_lshlrev_b32_e32 v178, 16, v24
	v_and_b32_e32 v179, 0xffff0000, v24
	v_lshlrev_b32_e32 v180, 16, v25
	v_and_b32_e32 v181, 0xffff0000, v25
	v_add_f32_e32 v174, v174, v178
	v_add_f32_e32 v175, v175, v179
	v_add_f32_e32 v176, v176, v180
	v_add_f32_e32 v177, v177, v181
	s_waitcnt lgkmcnt(1)
	v_lshlrev_b32_e32 v178, 16, v26
	v_and_b32_e32 v179, 0xffff0000, v26
	v_lshlrev_b32_e32 v180, 16, v27
	v_and_b32_e32 v181, 0xffff0000, v27
	v_add_f32_e32 v174, v174, v178
	v_add_f32_e32 v175, v175, v179
	v_add_f32_e32 v176, v176, v180
	v_add_f32_e32 v177, v177, v181
	v_lshlrev_b32_e32 v178, 16, v28
	v_and_b32_e32 v179, 0xffff0000, v28
	v_lshlrev_b32_e32 v180, 16, v29
	v_and_b32_e32 v181, 0xffff0000, v29
	v_add_f32_e32 v174, v174, v178
	v_add_f32_e32 v175, v175, v179
	v_add_f32_e32 v176, v176, v180
	v_add_f32_e32 v177, v177, v181
	s_waitcnt lgkmcnt(0)
	v_lshlrev_b32_e32 v178, 16, v30
	v_and_b32_e32 v179, 0xffff0000, v30
	v_lshlrev_b32_e32 v180, 16, v31
	v_and_b32_e32 v181, 0xffff0000, v31
	v_add_f32_e32 v174, v174, v178
	v_add_f32_e32 v175, v175, v179
	v_add_f32_e32 v176, v176, v180
	v_add_f32_e32 v177, v177, v181
	v_lshlrev_b32_e32 v178, 16, v32
	v_and_b32_e32 v179, 0xffff0000, v32
	v_lshlrev_b32_e32 v180, 16, v33
	v_and_b32_e32 v181, 0xffff0000, v33
	v_add_f32_e32 v174, v174, v178
	v_add_f32_e32 v175, v175, v179
	v_add_f32_e32 v176, v176, v180
	v_add_f32_e32 v177, v177, v181
	v_mul_f32_e32 v174, v186, v174
	v_mul_f32_e32 v175, v187, v175
	v_mul_f32_e32 v176, v188, v176
	v_mul_f32_e32 v177, v189, v177
	v_bfe_u32 v178, v174, 16, 1
	v_bfe_u32 v179, v175, 16, 1
	v_bfe_u32 v180, v176, 16, 1
	v_bfe_u32 v181, v177, 16, 1
	v_add3_u32 v174, v174, v178, s23
	v_add3_u32 v175, v175, v179, s23
	v_add3_u32 v176, v176, v180, s23
	v_add3_u32 v177, v177, v181, s23
	global_store_short_d16_hi v197, v174, s[20:21] offset:-4096
	global_store_short_d16_hi v197, v175, s[20:21]
	global_store_short_d16_hi v198, v176, s[20:21] offset:-4096
	global_store_short_d16_hi v198, v177, s[20:21]
	s_add_u32 s20, s20, 0x40000
	s_addc_u32 s21, s21, 0
	s_barrier
	s_branch .LBB0_718
